# 160-tile GEMM phases (FFN-out, out-proj): tile-to-XCD map changed so each XCD owns 5 complete M-tiles (pm=wgid/4,pn=wgid%4)
# speedup vs baseline: 1.0110x; 1.0027x over previous
.LBB0_263:
	v_writelane_b32 v253, s63, 9
	s_or_b64 exec, exec, s[6:7]
	s_cmpk_lt_i32 s2, 0xc8
	s_cselect_b64 s[4:5], -1, 0
	v_writelane_b32 v253, s4, 10
	s_mul_i32 s34, s67, s66
	s_mul_i32 s34, s34, s68
	v_writelane_b32 v253, s5, 11
	s_lshr_b32 s4, s3, 29
	s_add_i32 s4, s2, s4
	s_ashr_i32 s5, s4, 3
	s_and_b32 s4, s4, -8
	s_sub_i32 s7, s2, s4
	s_cmpk_lt_i32 s2, 0xf0
	s_cselect_b64 s[8:9], -1, 0
	v_writelane_b32 v253, s8, 12
	s_cmpk_lt_i32 s2, 0x150
	s_movk_i32 s81, 0x1080
	v_writelane_b32 v253, s9, 13
	s_cselect_b64 s[8:9], -1, 0
	s_cmpk_gt_i32 s2, 0x7f
	s_cselect_b64 s[56:57], -1, 0
	s_lshl_b32 s4, s2, 2
	s_add_i32 s77, s4, 0xfffffe80
	v_writelane_b32 v253, s8, 14
	s_cmpk_lt_i32 s2, 0xa0
	v_mov_b32_e32 v227, 0x358637bd
	v_writelane_b32 v253, s9, 15
	s_cselect_b64 s[8:9], -1, 0
	v_writelane_b32 v253, s8, 16
	s_cmpk_gt_i32 s2, 0x9f
	v_mov_b32_e32 v252, 1
	v_writelane_b32 v253, s9, 17
	s_cselect_b64 s[8:9], -1, 0
	v_writelane_b32 v253, s8, 18
	v_mbcnt_hi_u32_b32 v232, -1, v88
	v_mov_b32_e32 v233, 0x600
	v_writelane_b32 v253, s9, 19
	v_mov_b32_e32 v178, 0xf149f2ca
	v_readlane_b32 s4, v253, 0
	s_add_i32 s6, s4, 0xfffffb00
	s_cmpk_lt_i32 s2, 0x1e0
	v_writelane_b32 v253, s6, 20
	s_cselect_b64 s[8:9], -1, 0
	v_writelane_b32 v253, s8, 21
	s_cmpk_lt_i32 s2, 0x370
	s_movk_i32 s6, 0x6e
	v_writelane_b32 v253, s9, 22
	s_cselect_b64 s[8:9], -1, 0
	v_writelane_b32 v253, s8, 23
	s_cmpk_gt_i32 s2, 0x6f
	v_mov_b64_e32 v[180:181], 0xa0
	v_writelane_b32 v253, s9, 24
	s_cselect_b64 s[8:9], -1, 0
	v_writelane_b32 v253, s8, 25
	s_addk_i32 s4, 0xfc80
	s_cmp_lt_i32 s7, 0
	v_writelane_b32 v253, s9, 26
	v_writelane_b32 v253, s4, 27
	s_cselect_b32 s4, 26, 25
	s_mul_i32 s4, s7, s4
	s_cselect_b32 s8, 31, 30
	s_cselect_b32 s9, 43, 42
	s_cselect_b32 s10, 21, 20
	s_cselect_b32 s11, 61, 60
	s_cselect_b32 s12, 0x6f, s6
	s_add_i32 s4, s4, s5
	s_mul_hi_i32 s6, s4, 0x66666667
	s_lshr_b32 s13, s6, 31
	s_ashr_i32 s6, s6, 4
	s_add_i32 s6, s6, s13
	s_mul_i32 s13, s6, 40
	s_sub_i32 s4, s4, s13
	s_lshl_b32 s14, s6, 3
	s_bfe_i32 s6, s4, 0x80000
	s_bfe_u32 s6, s6, 0x3000c
	s_add_i32 s13, s4, s6
	s_bfe_i32 s6, s13, 0x80000
	s_and_b32 s13, s13, 0xf8
	s_sub_i32 s4, s4, s13
	s_sext_i32_i16 s15, s6
	s_sext_i32_i8 s4, s4
	s_mul_i32 s8, s7, s8
	s_add_i32 s19, s14, s4
	s_ashr_i32 s4, s15, 3
	s_add_i32 s8, s8, s5
	v_writelane_b32 v253, s4, 28
	s_mul_hi_i32 s4, s8, 0x2aaaaaab
	s_lshr_b32 s13, s4, 31
	s_ashr_i32 s4, s4, 3
	s_add_i32 s4, s4, s13
	s_mul_i32 s13, s4, 48
	s_sub_i32 s8, s8, s13
	s_lshl_b32 s14, s4, 3
	s_bfe_i32 s4, s8, 0x80000
	s_bfe_u32 s4, s4, 0x3000c
	s_add_i32 s13, s8, s4
	s_bfe_i32 s4, s13, 0x80000
	s_and_b32 s13, s13, 0xf8
	s_lshr_b32 s6, s15, 3
	s_sext_i32_i16 s15, s4
	s_sub_i32 s8, s8, s13
	s_lshr_b32 s4, s15, 3
	s_sext_i32_i8 s8, s8
	s_add_i32 s8, s14, s8
	s_ashr_i32 s13, s15, 3
	s_bfe_i64 s[14:15], s[4:5], 0x100000
	s_mul_i32 s4, s7, s9
	s_add_i32 s4, s4, s5
	s_ashr_i32 s9, s4, 31
	v_writelane_b32 v253, s13, 29
	s_lshr_b32 s9, s9, 26
	v_writelane_b32 v253, s8, 30
	s_ashr_i32 s8, s8, 31
	s_add_i32 s9, s4, s9
	v_writelane_b32 v253, s8, 31
	s_mul_i32 s8, s7, s10
	s_ashr_i32 s10, s9, 6
	s_andn2_b32 s9, s9, 63
	s_sub_i32 s9, s4, s9
	s_add_i32 s4, s8, s5
	s_mov_b32 s100, s4
	s_ashr_i32 s8, s4, 31
	s_lshl_b32 s13, s10, 3
	s_lshr_b32 s8, s8, 27
	v_writelane_b32 v253, s14, 32
	s_sub_i32 s10, 42, s13
	s_add_i32 s8, s4, s8
	v_writelane_b32 v253, s15, 33
	s_min_u32 s14, s10, 8
	s_ashr_i32 s10, s8, 5
	s_and_b32 s8, s8, 0xffe0
	s_sub_i32 s8, s4, s8
	s_bfe_i32 s4, s8, 0x80000
	s_bfe_u32 s4, s4, 0x3000c
	s_add_i32 s15, s8, s4
	s_bfe_i32 s4, s15, 0x80000
	s_and_b32 s15, s15, 0xf8
	s_sub_i32 s8, s8, s15
	s_lshl_b32 s10, s10, 3
	s_sext_i32_i16 s18, s4
	s_and_b32 s18, s100, 3
	s_lshl_b32 s18, s18, 3
	s_sext_i32_i8 s8, s8
	s_mul_i32 s11, s7, s11
	s_add_i32 s22, s10, s8
	s_lshr_b32 s22, s100, 2
	s_ashr_i32 s8, s18, 3
	s_add_i32 s11, s11, s5
	v_writelane_b32 v253, s8, 34
	s_mul_hi_i32 s8, s11, 0x2aaaaaab
	s_lshr_b32 s10, s8, 31
	s_ashr_i32 s8, s8, 4
	s_add_i32 s8, s8, s10
	s_mul_i32 s10, s8, 0x60
	s_sub_i32 s10, s11, s10
	s_lshl_b32 s15, s8, 3
	s_bfe_i32 s8, s10, 0x80000
	s_bfe_u32 s8, s8, 0x3000c
	s_add_i32 s11, s10, s8
	s_bfe_i32 s8, s11, 0x80000
	s_and_b32 s11, s11, 0xf8
	s_sub_i32 s10, s10, s11
	s_mul_i32 s7, s7, s12
	s_lshr_b32 s4, s18, 3
	s_sext_i32_i16 s18, s8
	s_sext_i32_i8 s10, s10
	s_add_i32 s7, s7, s5
	s_add_i32 s15, s15, s10
	s_ashr_i32 s10, s18, 3
	s_mul_hi_i32 s5, s7, 0x2e8ba2e9
	v_writelane_b32 v253, s10, 35
	s_lshr_b32 s10, s5, 31
	s_ashr_i32 s5, s5, 5
	s_add_i32 s5, s5, s10
	s_lshl_b32 s11, s5, 3
	s_mulk_i32 s5, 0xb0
	s_sub_i32 s5, s7, s5
	s_bfe_u32 s7, s5, 0x3001c
	s_add_i32 s7, s5, s7
	s_sext_i32_i16 s12, s7
	s_and_b32 s7, s7, 0xfff8
	s_sub_i32 s5, s5, s7
	s_sext_i32_i16 s5, s5
	s_ashr_i32 s7, s12, 3
	s_add_i32 s5, s11, s5
	v_writelane_b32 v253, s7, 36
	s_lshr_b32 s10, s12, 3
	v_writelane_b32 v253, s5, 37
	s_ashr_i32 s5, s5, 31
	v_writelane_b32 v253, s5, 38
	s_bfe_i64 s[10:11], s[10:11], 0x100000
	v_writelane_b32 v253, s10, 39
	s_ashr_i32 s5, s19, 31
	s_bfe_i64 s[6:7], s[6:7], 0x100000
	v_writelane_b32 v253, s11, 40
	v_writelane_b32 v253, s19, 41
	v_writelane_b32 v253, s5, 42
	v_writelane_b32 v253, s6, 43
	v_cvt_f32_ubyte0_e32 v1, s14
	s_ashr_i32 s5, s22, 31
	v_writelane_b32 v253, s7, 44
	v_writelane_b32 v253, s22, 45
	s_waitcnt lgkmcnt(0)
	v_cvt_f32_i32_e32 v0, s9
	v_rcp_iflag_f32_e32 v2, v1
	v_writelane_b32 v253, s5, 46
	s_bfe_i64 s[4:5], s[4:5], 0x100000
	v_writelane_b32 v253, s4, 47
	s_lshr_b32 s8, s18, 3
	v_mul_f32_e32 v2, v0, v2
	v_writelane_b32 v253, s5, 48
	v_writelane_b32 v253, s15, 49
	s_ashr_i32 s4, s15, 31
	v_writelane_b32 v253, s4, 50
	s_bfe_i64 s[4:5], s[8:9], 0x100000
	v_trunc_f32_e32 v2, v2
	v_writelane_b32 v253, s4, 51
	v_fma_f32 v0, -v2, v1, v0
	v_cvt_i32_f32_e32 v2, v2
	v_writelane_b32 v253, s5, 52
	s_ashr_i32 s4, s9, 30
	s_or_b32 s6, s4, 1
	v_cmp_ge_f32_e64 s[4:5], |v0|, v1
	s_and_b64 s[4:5], s[4:5], exec
	s_cselect_b32 s4, s6, 0
	v_readfirstlane_b32 s5, v2
	s_add_i32 s4, s5, s4
	s_sext_i32_i8 s5, s4
	s_mul_i32 s4, s4, s14
	s_sub_i32 s4, s9, s4
	s_sext_i32_i8 s4, s4
	v_writelane_b32 v253, s5, 53
	s_add_i32 s4, s13, s4
	v_writelane_b32 v253, s4, 54
	s_lshl_b32 s4, s66, 4
	v_writelane_b32 v253, s4, 6
	s_lshl_b32 s4, s66, 5
	v_writelane_b32 v253, s4, 55
	s_mul_i32 s4, s66, 0xf000
	s_mul_hi_i32 s5, s64, 0x600
	v_writelane_b32 v253, s4, 56
	s_ashr_i32 s65, s64, 31
	s_lshl_b64 s[6:7], s[64:65], 7
	v_writelane_b32 v253, s5, 57
	s_mul_i32 s4, s66, 0x29400
	s_mul_hi_i32 s5, s64, 0x1080
	v_writelane_b32 v253, s4, 58
	s_movk_i32 s19, 0xc00
	s_movk_i32 s18, 0x2000
	v_writelane_b32 v253, s5, 59
	s_add_i32 s4, 0, 0x20020
	v_writelane_b32 v253, s4, 60
	s_add_i32 s4, 0, 0x20024
	v_writelane_b32 v253, s4, 61
	s_mov_b32 s4, 0
	v_writelane_b32 v253, s4, 62
	v_writelane_b32 v253, s6, 63
	s_movk_i32 s5, 0x1f70
	s_mov_b32 s4, s64
	v_writelane_b32 v254, s7, 0
	s_lshl_b64 s[6:7], s[64:65], 2
	v_writelane_b32 v254, s6, 1
	v_writelane_b32 v253, s4, 7
	v_mov_b32_e32 v1, 0
	v_writelane_b32 v254, s7, 2
	s_lshl_b64 s[6:7], s[64:65], 9
	v_writelane_b32 v254, s6, 3
	v_mov_b64_e32 v[182:183], 0x9f
	v_mov_b64_e32 v[184:185], 0x1e0
	v_writelane_b32 v254, s7, 4
	v_writelane_b32 v254, s56, 5
	v_mov_b64_e32 v[186:187], 0x1df
	v_mov_b64_e32 v[188:189], 0x370
	v_writelane_b32 v254, s57, 6
	v_mov_b64_e32 v[190:191], 0x36f
	s_mov_b32 s51, 0xf149f2ca
	s_mov_b32 s46, 0x3e16c740
	s_movk_i32 s96, 0x1f80
	s_movk_i32 s50, 0x1f60
	s_movk_i32 s66, 0x1f50
	s_movk_i32 s33, 0x1600
	s_mov_b32 s47, 0x2c000
	s_mov_b32 s23, 0x3e38aa3b
	s_mov_b32 s59, 0
	v_writelane_b32 v253, s5, 8
	s_mov_b32 s64, 0x16000
	s_mov_b64 s[24:25], 0
	s_mov_b64 s[72:73], 0x80
	v_writelane_b32 v254, s77, 7
	s_barrier
	s_branch .LBB0_265
